# SwiGLU epilogue regenerated with independent 8-wide batches; accumulator zeroing folded into it (header zeroing skipped after first tile)
# speedup vs baseline: 1.0054x; 1.0054x over previous
.LBB0_1334:
	s_ashr_i32 s45, s44, 31
	s_lshl_b64 s[20:21], s[44:45], 19
	s_add_u32 s46, s4, s20
	s_addc_u32 s47, s5, s21
	s_and_b64 s[20:21], s[36:37], exec
	s_cselect_b32 s45, s47, s13
	s_cselect_b32 s58, s46, s12
	s_ashr_i32 s43, s42, 31
	s_lshl_b64 s[20:21], s[42:43], 19
	s_add_u32 s48, s26, s20
	s_addc_u32 s49, s27, s21
	s_and_b64 s[20:21], s[36:37], exec
	s_cselect_b32 s43, s49, s1
	s_cselect_b32 s59, s48, s0
	s_add_u32 s12, s12, 0x40080
	s_addc_u32 s13, s13, 0
	s_add_u32 s60, s0, 0x100
	v_mov_b32_e32 v0, 0
	s_addc_u32 s61, s1, 0
	s_mov_b32 s62, -2
	s_cmp_lg_u32 s55, 1
	s_cbranch_scc1 .Lgu_nozero
	v_mov_b32_e32 v1, v0
	v_mov_b32_e32 v2, v0
	v_mov_b32_e32 v3, v0
	v_mov_b32_e32 v8, v0
	v_mov_b32_e32 v9, v0
	v_mov_b32_e32 v10, v0
	v_mov_b32_e32 v11, v0
	v_mov_b32_e32 v16, v0
	v_mov_b32_e32 v17, v0
	v_mov_b32_e32 v18, v0
	v_mov_b32_e32 v19, v0
	v_mov_b32_e32 v24, v0
	v_mov_b32_e32 v25, v0
	v_mov_b32_e32 v26, v0
	v_mov_b32_e32 v27, v0
	v_mov_b32_e32 v32, v0
	v_mov_b32_e32 v33, v0
	v_mov_b32_e32 v34, v0
	v_mov_b32_e32 v35, v0
	v_mov_b32_e32 v40, v0
	v_mov_b32_e32 v41, v0
	v_mov_b32_e32 v42, v0
	v_mov_b32_e32 v43, v0
	v_mov_b32_e32 v48, v0
	v_mov_b32_e32 v49, v0
	v_mov_b32_e32 v50, v0
	v_mov_b32_e32 v51, v0
	v_mov_b32_e32 v56, v0
	v_mov_b32_e32 v57, v0
	v_mov_b32_e32 v58, v0
	v_mov_b32_e32 v59, v0
	v_mov_b32_e32 v4, v0
	v_mov_b32_e32 v5, v0
	v_mov_b32_e32 v6, v0
	v_mov_b32_e32 v7, v0
	v_mov_b32_e32 v12, v0
	v_mov_b32_e32 v13, v0
	v_mov_b32_e32 v14, v0
	v_mov_b32_e32 v15, v0
	v_mov_b32_e32 v20, v0
	v_mov_b32_e32 v21, v0
	v_mov_b32_e32 v22, v0
	v_mov_b32_e32 v23, v0
	v_mov_b32_e32 v28, v0
	v_mov_b32_e32 v29, v0
	v_mov_b32_e32 v30, v0
	v_mov_b32_e32 v31, v0
	v_mov_b32_e32 v36, v0
	v_mov_b32_e32 v37, v0
	v_mov_b32_e32 v38, v0
	v_mov_b32_e32 v39, v0
	v_mov_b32_e32 v44, v0
	v_mov_b32_e32 v45, v0
	v_mov_b32_e32 v46, v0
	v_mov_b32_e32 v47, v0
	v_mov_b32_e32 v52, v0
	v_mov_b32_e32 v53, v0
	v_mov_b32_e32 v54, v0
	v_mov_b32_e32 v55, v0
	v_mov_b32_e32 v60, v0
	v_mov_b32_e32 v61, v0
	v_mov_b32_e32 v62, v0
	v_mov_b32_e32 v63, v0
	v_mov_b32_e32 v64, v0
	v_mov_b32_e32 v65, v0
	v_mov_b32_e32 v66, v0
	v_mov_b32_e32 v67, v0
	v_mov_b32_e32 v72, v0
	v_mov_b32_e32 v73, v0
	v_mov_b32_e32 v74, v0
	v_mov_b32_e32 v75, v0
	v_mov_b32_e32 v80, v0
	v_mov_b32_e32 v81, v0
	v_mov_b32_e32 v82, v0
	v_mov_b32_e32 v83, v0
	v_mov_b32_e32 v88, v0
	v_mov_b32_e32 v89, v0
	v_mov_b32_e32 v90, v0
	v_mov_b32_e32 v91, v0
	v_mov_b32_e32 v96, v0
	v_mov_b32_e32 v97, v0
	v_mov_b32_e32 v98, v0
	v_mov_b32_e32 v99, v0
	v_mov_b32_e32 v104, v0
	v_mov_b32_e32 v105, v0
	v_mov_b32_e32 v106, v0
	v_mov_b32_e32 v107, v0
	v_mov_b32_e32 v112, v0
	v_mov_b32_e32 v113, v0
	v_mov_b32_e32 v114, v0
	v_mov_b32_e32 v115, v0
	v_mov_b32_e32 v120, v0
	v_mov_b32_e32 v121, v0
	v_mov_b32_e32 v122, v0
	v_mov_b32_e32 v123, v0
	v_mov_b32_e32 v68, v0
	v_mov_b32_e32 v69, v0
	v_mov_b32_e32 v70, v0
	v_mov_b32_e32 v71, v0
	v_mov_b32_e32 v76, v0
	v_mov_b32_e32 v77, v0
	v_mov_b32_e32 v78, v0
	v_mov_b32_e32 v79, v0
	v_mov_b32_e32 v84, v0
	v_mov_b32_e32 v85, v0
	v_mov_b32_e32 v86, v0
	v_mov_b32_e32 v87, v0
	v_mov_b32_e32 v92, v0
	v_mov_b32_e32 v93, v0
	v_mov_b32_e32 v94, v0
	v_mov_b32_e32 v95, v0
	v_mov_b32_e32 v100, v0
	v_mov_b32_e32 v101, v0
	v_mov_b32_e32 v102, v0
	v_mov_b32_e32 v103, v0
	v_mov_b32_e32 v108, v0
	v_mov_b32_e32 v109, v0
	v_mov_b32_e32 v110, v0
	v_mov_b32_e32 v111, v0
	v_mov_b32_e32 v116, v0
	v_mov_b32_e32 v117, v0
	v_mov_b32_e32 v118, v0
	v_mov_b32_e32 v119, v0
	v_mov_b32_e32 v124, v0
	v_mov_b32_e32 v125, v0
	v_mov_b32_e32 v126, v0
	v_mov_b32_e32 v127, v0
.Lgu_nozero:
.LBB0_1335:
	s_add_u32 s0, s12, 0xfffc0080
	s_addc_u32 s1, s13, -1
	s_add_i32 s63, 0, 0x10000
	s_cmp_eq_u32 s62, 12
	s_cselect_b32 s21, s45, s1
	s_cselect_b32 s20, s58, s0
	v_add_u32_e32 v154, s63, v157
	s_cselect_b32 s1, s43, s61
	s_cselect_b32 s0, s59, s60
	s_add_i32 s66, 0, 0x14000
	ds_read_b128 v[160:163], v154
	ds_read_b128 v[164:167], v154 offset:1024
	ds_read_b128 v[168:171], v154 offset:2048
	ds_read_b128 v[172:175], v154 offset:3072
	v_add_u32_e32 v154, s66, v157
	ds_read_b128 v[190:193], v154
	ds_read_b128 v[194:197], v154 offset:1024
	ds_read_b128 v[198:201], v154 offset:2048
	ds_read_b128 v[202:205], v154 offset:3072
	v_lshl_add_u64 v[154:155], s[12:13], 0, v[134:135]
	s_add_i32 m0, s35, 0xc000
	ds_read_b128 v[206:209], v159
	ds_read_b128 v[210:213], v159 offset:1024
	ds_read_b128 v[214:217], v159 offset:2048
	ds_read_b128 v[218:221], v159 offset:3072
	ds_read_b128 v[222:225], v159 offset:4096
	ds_read_b128 v[226:229], v159 offset:5120
	ds_read_b128 v[230:233], v159 offset:6144
	ds_read_b128 v[234:237], v159 offset:7168
	global_load_lds_dwordx4 v[154:155], off
	v_lshl_add_u64 v[154:155], s[12:13], 0, v[152:153]
	s_add_i32 m0, s35, 0xe000
	s_nop 0
	global_load_lds_dwordx4 v[154:155], off
	s_waitcnt vmcnt(8)
	s_waitcnt lgkmcnt(0)
	s_barrier
	s_setprio 1
	s_waitcnt lgkmcnt(0)
	v_mfma_f32_16x16x32_bf16 v[124:127], v[160:163], v[206:209], v[124:127]
	v_mfma_f32_16x16x32_bf16 v[116:119], v[168:171], v[206:209], v[116:119]
	v_mfma_f32_16x16x32_bf16 v[108:111], v[160:163], v[214:217], v[108:111]
	v_mfma_f32_16x16x32_bf16 v[100:103], v[168:171], v[214:217], v[100:103]
	v_mfma_f32_16x16x32_bf16 v[92:95], v[160:163], v[222:225], v[92:95]
	v_mfma_f32_16x16x32_bf16 v[84:87], v[168:171], v[222:225], v[84:87]
	v_mfma_f32_16x16x32_bf16 v[76:79], v[160:163], v[230:233], v[76:79]
	v_mfma_f32_16x16x32_bf16 v[68:71], v[168:171], v[230:233], v[68:71]
	v_mfma_f32_16x16x32_bf16 v[124:127], v[164:167], v[210:213], v[124:127]
	v_mfma_f32_16x16x32_bf16 v[116:119], v[172:175], v[210:213], v[116:119]
	v_mfma_f32_16x16x32_bf16 v[108:111], v[164:167], v[218:221], v[108:111]
	v_mfma_f32_16x16x32_bf16 v[100:103], v[172:175], v[218:221], v[100:103]
	v_mfma_f32_16x16x32_bf16 v[92:95], v[164:167], v[226:229], v[92:95]
	v_mfma_f32_16x16x32_bf16 v[84:87], v[172:175], v[226:229], v[84:87]
	v_mfma_f32_16x16x32_bf16 v[76:79], v[164:167], v[234:237], v[76:79]
	v_mfma_f32_16x16x32_bf16 v[68:71], v[172:175], v[234:237], v[68:71]
	s_setprio 0
	s_setprio 1
	v_mfma_f32_16x16x32_bf16 v[120:123], v[190:193], v[206:209], v[120:123]
	v_mfma_f32_16x16x32_bf16 v[112:115], v[198:201], v[206:209], v[112:115]
	v_mfma_f32_16x16x32_bf16 v[104:107], v[190:193], v[214:217], v[104:107]
	v_mfma_f32_16x16x32_bf16 v[96:99], v[198:201], v[214:217], v[96:99]
	v_mfma_f32_16x16x32_bf16 v[88:91], v[190:193], v[222:225], v[88:91]
	v_mfma_f32_16x16x32_bf16 v[80:83], v[198:201], v[222:225], v[80:83]
	v_mfma_f32_16x16x32_bf16 v[72:75], v[190:193], v[230:233], v[72:75]
	v_mfma_f32_16x16x32_bf16 v[64:67], v[198:201], v[230:233], v[64:67]
	v_mfma_f32_16x16x32_bf16 v[120:123], v[194:197], v[210:213], v[120:123]
	v_mfma_f32_16x16x32_bf16 v[112:115], v[202:205], v[210:213], v[112:115]
	v_mfma_f32_16x16x32_bf16 v[104:107], v[194:197], v[218:221], v[104:107]
	v_mfma_f32_16x16x32_bf16 v[96:99], v[202:205], v[218:221], v[96:99]
	v_mfma_f32_16x16x32_bf16 v[88:91], v[194:197], v[226:229], v[88:91]
	v_mfma_f32_16x16x32_bf16 v[80:83], v[202:205], v[226:229], v[80:83]
	v_mfma_f32_16x16x32_bf16 v[72:75], v[194:197], v[234:237], v[72:75]
	v_mfma_f32_16x16x32_bf16 v[64:67], v[202:205], v[234:237], v[64:67]
	s_setprio 0
	s_barrier
	s_add_i32 s63, s63, s34
	v_lshl_add_u64 v[154:155], s[0:1], 0, v[138:139]
	s_mov_b32 m0, s63
	ds_read_b128 v[206:209], v159 offset:16384
	ds_read_b128 v[210:213], v159 offset:17408
	ds_read_b128 v[214:217], v159 offset:18432
	ds_read_b128 v[218:221], v159 offset:19456
	ds_read_b128 v[222:225], v159 offset:20480
	ds_read_b128 v[226:229], v159 offset:21504
	ds_read_b128 v[230:233], v159 offset:22528
	ds_read_b128 v[234:237], v159 offset:23552
	global_load_lds_dwordx4 v[154:155], off
	s_add_i32 m0, s63, 0x2000
	s_add_u32 s64, s0, 0x40000
	v_lshl_add_u64 v[238:239], s[0:1], 0, v[128:129]
	s_addc_u32 s65, s1, 0
	s_add_i32 s63, s66, s34
	global_load_lds_dwordx4 v[238:239], off
	v_lshl_add_u64 v[240:241], s[64:65], 0, v[138:139]
	s_mov_b32 m0, s63
	v_lshl_add_u64 v[242:243], s[20:21], 0, v[130:131]
	global_load_lds_dwordx4 v[240:241], off
	v_lshl_add_u64 v[240:241], s[64:65], 0, v[128:129]
	s_add_i32 m0, s63, 0x2000
	s_nop 0
	global_load_lds_dwordx4 v[240:241], off
	v_lshl_add_u64 v[240:241], s[20:21], 0, v[132:133]
	s_mov_b32 m0, s35
	s_nop 0
	global_load_lds_dwordx4 v[240:241], off
	s_mov_b32 m0, s50
	s_nop 0
	global_load_lds_dwordx4 v[242:243], off
	s_waitcnt vmcnt(8)
	s_waitcnt lgkmcnt(0)
	s_barrier
	s_setprio 1
	s_waitcnt lgkmcnt(0)
	v_mfma_f32_16x16x32_bf16 v[60:63], v[160:163], v[206:209], v[60:63]
	v_mfma_f32_16x16x32_bf16 v[52:55], v[168:171], v[206:209], v[52:55]
	v_mfma_f32_16x16x32_bf16 v[44:47], v[160:163], v[214:217], v[44:47]
	v_mfma_f32_16x16x32_bf16 v[36:39], v[168:171], v[214:217], v[36:39]
	v_mfma_f32_16x16x32_bf16 v[28:31], v[160:163], v[222:225], v[28:31]
	v_mfma_f32_16x16x32_bf16 v[20:23], v[168:171], v[222:225], v[20:23]
	v_mfma_f32_16x16x32_bf16 v[12:15], v[160:163], v[230:233], v[12:15]
	v_mfma_f32_16x16x32_bf16 v[4:7], v[168:171], v[230:233], v[4:7]
	v_mfma_f32_16x16x32_bf16 v[60:63], v[164:167], v[210:213], v[60:63]
	v_mfma_f32_16x16x32_bf16 v[52:55], v[172:175], v[210:213], v[52:55]
	v_mfma_f32_16x16x32_bf16 v[44:47], v[164:167], v[218:221], v[44:47]
	v_mfma_f32_16x16x32_bf16 v[36:39], v[172:175], v[218:221], v[36:39]
	v_mfma_f32_16x16x32_bf16 v[28:31], v[164:167], v[226:229], v[28:31]
	v_mfma_f32_16x16x32_bf16 v[20:23], v[172:175], v[226:229], v[20:23]
	v_mfma_f32_16x16x32_bf16 v[12:15], v[164:167], v[234:237], v[12:15]
	v_mfma_f32_16x16x32_bf16 v[4:7], v[172:175], v[234:237], v[4:7]
	s_setprio 0
	s_setprio 1
	v_mfma_f32_16x16x32_bf16 v[56:59], v[190:193], v[206:209], v[56:59]
	v_mfma_f32_16x16x32_bf16 v[48:51], v[198:201], v[206:209], v[48:51]
	v_mfma_f32_16x16x32_bf16 v[40:43], v[190:193], v[214:217], v[40:43]
	v_mfma_f32_16x16x32_bf16 v[32:35], v[198:201], v[214:217], v[32:35]
	v_mfma_f32_16x16x32_bf16 v[24:27], v[190:193], v[222:225], v[24:27]
	v_mfma_f32_16x16x32_bf16 v[16:19], v[198:201], v[222:225], v[16:19]
	v_mfma_f32_16x16x32_bf16 v[8:11], v[190:193], v[230:233], v[8:11]
	v_mfma_f32_16x16x32_bf16 v[0:3], v[198:201], v[230:233], v[0:3]
	v_mfma_f32_16x16x32_bf16 v[56:59], v[194:197], v[210:213], v[56:59]
	v_mfma_f32_16x16x32_bf16 v[48:51], v[202:205], v[210:213], v[48:51]
	v_mfma_f32_16x16x32_bf16 v[40:43], v[194:197], v[218:221], v[40:43]
	v_mfma_f32_16x16x32_bf16 v[32:35], v[202:205], v[218:221], v[32:35]
	v_mfma_f32_16x16x32_bf16 v[24:27], v[194:197], v[226:229], v[24:27]
	v_mfma_f32_16x16x32_bf16 v[16:19], v[202:205], v[226:229], v[16:19]
	v_mfma_f32_16x16x32_bf16 v[8:11], v[194:197], v[234:237], v[8:11]
	v_mfma_f32_16x16x32_bf16 v[0:3], v[202:205], v[234:237], v[0:3]
	s_setprio 0
	s_barrier
	s_add_i32 s63, 0, 0x18000
	s_add_i32 s64, 0, 0x1c000
	v_add_u32_e32 v172, s63, v157
	v_add_u32_e32 v202, s64, v157
	ds_read_b128 v[160:163], v172
	ds_read_b128 v[164:167], v172 offset:1024
	ds_read_b128 v[168:171], v172 offset:2048
	ds_read_b128 v[172:175], v172 offset:3072
	ds_read_b128 v[190:193], v202
	ds_read_b128 v[194:197], v202 offset:1024
	ds_read_b128 v[198:201], v202 offset:2048
	ds_read_b128 v[202:205], v202 offset:3072
	s_add_u32 s20, s20, 0x40000
	s_addc_u32 s21, s21, 0
	s_mov_b32 m0, s51
	v_lshl_add_u64 v[244:245], s[20:21], 0, v[132:133]
	ds_read_b128 v[206:209], v159 offset:32768
	ds_read_b128 v[210:213], v159 offset:33792
	ds_read_b128 v[214:217], v159 offset:34816
	ds_read_b128 v[218:221], v159 offset:35840
	ds_read_b128 v[222:225], v159 offset:36864
	ds_read_b128 v[226:229], v159 offset:37888
	ds_read_b128 v[230:233], v159 offset:38912
	ds_read_b128 v[234:237], v159 offset:39936
	global_load_lds_dwordx4 v[244:245], off
	v_lshl_add_u64 v[244:245], s[20:21], 0, v[130:131]
	s_mov_b32 m0, s52
	s_nop 0
	global_load_lds_dwordx4 v[244:245], off
	s_waitcnt vmcnt(8)
	s_waitcnt lgkmcnt(0)
	s_barrier
	s_setprio 1
	s_waitcnt lgkmcnt(0)
	v_mfma_f32_16x16x32_bf16 v[124:127], v[160:163], v[206:209], v[124:127]
	v_mfma_f32_16x16x32_bf16 v[116:119], v[168:171], v[206:209], v[116:119]
	v_mfma_f32_16x16x32_bf16 v[108:111], v[160:163], v[214:217], v[108:111]
	v_mfma_f32_16x16x32_bf16 v[100:103], v[168:171], v[214:217], v[100:103]
	v_mfma_f32_16x16x32_bf16 v[92:95], v[160:163], v[222:225], v[92:95]
	v_mfma_f32_16x16x32_bf16 v[84:87], v[168:171], v[222:225], v[84:87]
	v_mfma_f32_16x16x32_bf16 v[76:79], v[160:163], v[230:233], v[76:79]
	v_mfma_f32_16x16x32_bf16 v[68:71], v[168:171], v[230:233], v[68:71]
	v_mfma_f32_16x16x32_bf16 v[124:127], v[164:167], v[210:213], v[124:127]
	v_mfma_f32_16x16x32_bf16 v[116:119], v[172:175], v[210:213], v[116:119]
	v_mfma_f32_16x16x32_bf16 v[108:111], v[164:167], v[218:221], v[108:111]
	v_mfma_f32_16x16x32_bf16 v[100:103], v[172:175], v[218:221], v[100:103]
	v_mfma_f32_16x16x32_bf16 v[92:95], v[164:167], v[226:229], v[92:95]
	v_mfma_f32_16x16x32_bf16 v[84:87], v[172:175], v[226:229], v[84:87]
	v_mfma_f32_16x16x32_bf16 v[76:79], v[164:167], v[234:237], v[76:79]
	v_mfma_f32_16x16x32_bf16 v[68:71], v[172:175], v[234:237], v[68:71]
	s_setprio 0
	s_setprio 1
	v_mfma_f32_16x16x32_bf16 v[120:123], v[190:193], v[206:209], v[120:123]
	v_mfma_f32_16x16x32_bf16 v[112:115], v[198:201], v[206:209], v[112:115]
	v_mfma_f32_16x16x32_bf16 v[104:107], v[190:193], v[214:217], v[104:107]
	v_mfma_f32_16x16x32_bf16 v[96:99], v[198:201], v[214:217], v[96:99]
	v_mfma_f32_16x16x32_bf16 v[88:91], v[190:193], v[222:225], v[88:91]
	v_mfma_f32_16x16x32_bf16 v[80:83], v[198:201], v[222:225], v[80:83]
	v_mfma_f32_16x16x32_bf16 v[72:75], v[190:193], v[230:233], v[72:75]
	v_mfma_f32_16x16x32_bf16 v[64:67], v[198:201], v[230:233], v[64:67]
	v_mfma_f32_16x16x32_bf16 v[120:123], v[194:197], v[210:213], v[120:123]
	v_mfma_f32_16x16x32_bf16 v[112:115], v[202:205], v[210:213], v[112:115]
	v_mfma_f32_16x16x32_bf16 v[104:107], v[194:197], v[218:221], v[104:107]
	v_mfma_f32_16x16x32_bf16 v[96:99], v[202:205], v[218:221], v[96:99]
	v_mfma_f32_16x16x32_bf16 v[88:91], v[194:197], v[226:229], v[88:91]
	v_mfma_f32_16x16x32_bf16 v[80:83], v[202:205], v[226:229], v[80:83]
	v_mfma_f32_16x16x32_bf16 v[72:75], v[194:197], v[234:237], v[72:75]
	v_mfma_f32_16x16x32_bf16 v[64:67], v[202:205], v[234:237], v[64:67]
	s_setprio 0
	s_barrier
	s_add_i32 s20, s63, s34
	v_lshl_add_u64 v[154:155], v[154:155], 0, s[16:17]
	s_mov_b32 m0, s20
	ds_read_b128 v[206:209], v159 offset:49152
	ds_read_b128 v[210:213], v159 offset:50176
	ds_read_b128 v[214:217], v159 offset:51200
	ds_read_b128 v[218:221], v159 offset:52224
	ds_read_b128 v[222:225], v159 offset:53248
	ds_read_b128 v[226:229], v159 offset:54272
	ds_read_b128 v[230:233], v159 offset:55296
	ds_read_b128 v[234:237], v159 offset:56320
	global_load_lds_dwordx4 v[154:155], off
	s_add_i32 m0, s20, 0x2000
	s_add_u32 s0, s0, 0x40080
	v_lshl_add_u64 v[154:155], v[238:239], 0, s[16:17]
	s_addc_u32 s1, s1, 0
	s_add_i32 s20, s64, s34
	global_load_lds_dwordx4 v[154:155], off
	v_lshl_add_u64 v[154:155], s[0:1], 0, v[138:139]
	s_mov_b32 m0, s20
	s_nop 0
	global_load_lds_dwordx4 v[154:155], off
	v_lshl_add_u64 v[154:155], s[0:1], 0, v[128:129]
	s_add_i32 m0, s20, 0x2000
	s_nop 0
	global_load_lds_dwordx4 v[154:155], off
	v_lshl_add_u64 v[154:155], v[240:241], 0, s[16:17]
	s_mov_b32 m0, s53
	s_nop 0
	global_load_lds_dwordx4 v[154:155], off
	v_lshl_add_u64 v[154:155], v[242:243], 0, s[16:17]
	s_mov_b32 m0, s54
	s_nop 0
	global_load_lds_dwordx4 v[154:155], off
	s_waitcnt vmcnt(8)
	s_waitcnt lgkmcnt(0)
	s_barrier
	s_setprio 1
	s_waitcnt lgkmcnt(0)
	v_mfma_f32_16x16x32_bf16 v[60:63], v[160:163], v[206:209], v[60:63]
	v_mfma_f32_16x16x32_bf16 v[52:55], v[168:171], v[206:209], v[52:55]
	v_mfma_f32_16x16x32_bf16 v[44:47], v[160:163], v[214:217], v[44:47]
	v_mfma_f32_16x16x32_bf16 v[36:39], v[168:171], v[214:217], v[36:39]
	v_mfma_f32_16x16x32_bf16 v[28:31], v[160:163], v[222:225], v[28:31]
	v_mfma_f32_16x16x32_bf16 v[20:23], v[168:171], v[222:225], v[20:23]
	v_mfma_f32_16x16x32_bf16 v[12:15], v[160:163], v[230:233], v[12:15]
	v_mfma_f32_16x16x32_bf16 v[4:7], v[168:171], v[230:233], v[4:7]
	v_mfma_f32_16x16x32_bf16 v[60:63], v[164:167], v[210:213], v[60:63]
	v_mfma_f32_16x16x32_bf16 v[52:55], v[172:175], v[210:213], v[52:55]
	v_mfma_f32_16x16x32_bf16 v[44:47], v[164:167], v[218:221], v[44:47]
	v_mfma_f32_16x16x32_bf16 v[36:39], v[172:175], v[218:221], v[36:39]
	v_mfma_f32_16x16x32_bf16 v[28:31], v[164:167], v[226:229], v[28:31]
	v_mfma_f32_16x16x32_bf16 v[20:23], v[172:175], v[226:229], v[20:23]
	v_mfma_f32_16x16x32_bf16 v[12:15], v[164:167], v[234:237], v[12:15]
	v_mfma_f32_16x16x32_bf16 v[4:7], v[172:175], v[234:237], v[4:7]
	s_setprio 0
	s_setprio 1
	v_mfma_f32_16x16x32_bf16 v[56:59], v[190:193], v[206:209], v[56:59]
	v_mfma_f32_16x16x32_bf16 v[48:51], v[198:201], v[206:209], v[48:51]
	v_mfma_f32_16x16x32_bf16 v[40:43], v[190:193], v[214:217], v[40:43]
	v_mfma_f32_16x16x32_bf16 v[32:35], v[198:201], v[214:217], v[32:35]
	v_mfma_f32_16x16x32_bf16 v[24:27], v[190:193], v[222:225], v[24:27]
	v_mfma_f32_16x16x32_bf16 v[16:19], v[198:201], v[222:225], v[16:19]
	v_mfma_f32_16x16x32_bf16 v[8:11], v[190:193], v[230:233], v[8:11]
	v_mfma_f32_16x16x32_bf16 v[0:3], v[198:201], v[230:233], v[0:3]
	v_mfma_f32_16x16x32_bf16 v[56:59], v[194:197], v[210:213], v[56:59]
	v_mfma_f32_16x16x32_bf16 v[48:51], v[202:205], v[210:213], v[48:51]
	v_mfma_f32_16x16x32_bf16 v[40:43], v[194:197], v[218:221], v[40:43]
	v_mfma_f32_16x16x32_bf16 v[32:35], v[202:205], v[218:221], v[32:35]
	v_mfma_f32_16x16x32_bf16 v[24:27], v[194:197], v[226:229], v[24:27]
	v_mfma_f32_16x16x32_bf16 v[16:19], v[202:205], v[226:229], v[16:19]
	v_mfma_f32_16x16x32_bf16 v[8:11], v[194:197], v[234:237], v[8:11]
	v_mfma_f32_16x16x32_bf16 v[0:3], v[202:205], v[234:237], v[0:3]
	s_setprio 0
	s_barrier
	s_add_i32 s62, s62, 2
	s_add_u32 s12, s12, 0x100
	s_addc_u32 s13, s13, 0
	s_add_u32 s60, s60, 0x100
	s_addc_u32 s61, s61, 0
	s_cmp_gt_u32 s62, 13
	s_cbranch_scc0 .LBB0_1335
	s_and_b64 vcc, exec, s[40:41]
	s_cbranch_vccz .LBB0_1338
	s_barrier
.LBB0_1338:
	v_lshl_or_b32 v162, s56, 7, v158
	v_lshl_add_u32 v160, s57, 8, v156
	v_ashrrev_i32_e32 v163, 31, v162
	v_mov_b64_e32 v[154:155], s[6:7]
	v_mov_b32_e32 v168, s76
	v_mov_b32_e32 v169, 0
	v_lshlrev_b64 v[166:167], 1, v[162:163]
	v_mad_i64_i32 v[164:165], vcc, v160, s76, v[154:155]
	v_lshlrev_b32_e32 v168, 4, v168
	v_mul_f32_e32 v190, 0xbfb8aa3b, v124
	v_mul_f32_e32 v191, 0xbfb8aa3b, v125
	v_mul_f32_e32 v192, 0xbfb8aa3b, v126
	v_mul_f32_e32 v193, 0xbfb8aa3b, v127
	v_mul_f32_e32 v194, 0xbfb8aa3b, v116
	v_mul_f32_e32 v195, 0xbfb8aa3b, v117
	v_mul_f32_e32 v196, 0xbfb8aa3b, v118
	v_mul_f32_e32 v197, 0xbfb8aa3b, v119
	v_lshl_add_u64 v[200:201], v[164:165], 0, v[166:167]
	v_exp_f32_e32 v190, v190
	v_exp_f32_e32 v191, v191
	v_exp_f32_e32 v192, v192
	v_exp_f32_e32 v193, v193
	v_exp_f32_e32 v194, v194
	v_exp_f32_e32 v195, v195
	v_exp_f32_e32 v196, v196
	v_exp_f32_e32 v197, v197
	v_add_f32_e32 v190, 1.0, v190
	v_add_f32_e32 v191, 1.0, v191
	v_add_f32_e32 v192, 1.0, v192
	v_add_f32_e32 v193, 1.0, v193
	v_add_f32_e32 v194, 1.0, v194
	v_add_f32_e32 v195, 1.0, v195
	v_add_f32_e32 v196, 1.0, v196
	v_add_f32_e32 v197, 1.0, v197
	v_rcp_f32_e32 v190, v190
	v_rcp_f32_e32 v191, v191
	v_rcp_f32_e32 v192, v192
	v_rcp_f32_e32 v193, v193
	v_rcp_f32_e32 v194, v194
	v_rcp_f32_e32 v195, v195
	v_rcp_f32_e32 v196, v196
	v_rcp_f32_e32 v197, v197
	v_mul_f32_e32 v124, v124, v190
	v_mul_f32_e32 v125, v125, v191
	v_mul_f32_e32 v126, v126, v192
	v_mul_f32_e32 v127, v127, v193
	v_mul_f32_e32 v116, v116, v194
	v_mul_f32_e32 v117, v117, v195
	v_mul_f32_e32 v118, v118, v196
	v_mul_f32_e32 v119, v119, v197
	v_mul_f32_e32 v124, v124, v120
	v_mul_f32_e32 v125, v125, v121
	v_mul_f32_e32 v126, v126, v122
	v_mul_f32_e32 v127, v127, v123
	v_mul_f32_e32 v116, v116, v112
	v_mul_f32_e32 v117, v117, v113
	v_mul_f32_e32 v118, v118, v114
	v_mul_f32_e32 v119, v119, v115
	v_cvt_pk_bf16_f32 v120, v124, v125
	v_cvt_pk_bf16_f32 v121, v126, v127
	v_cvt_pk_bf16_f32 v122, v116, v117
	v_cvt_pk_bf16_f32 v123, v118, v119
	global_store_dwordx4 v[200:201], v[120:123], off
	v_mov_b32_e32 v124, 0
	v_mov_b32_e32 v125, 0
	v_mov_b32_e32 v126, 0
	v_mov_b32_e32 v127, 0
	v_mov_b32_e32 v116, 0
	v_mov_b32_e32 v117, 0
	v_mov_b32_e32 v118, 0
	v_mov_b32_e32 v119, 0
	v_mov_b32_e32 v112, 0
	v_mov_b32_e32 v113, 0
	v_mov_b32_e32 v114, 0
	v_mov_b32_e32 v115, 0
	v_mul_f32_e32 v216, 0xbfb8aa3b, v108
	v_mul_f32_e32 v217, 0xbfb8aa3b, v109
	v_mul_f32_e32 v218, 0xbfb8aa3b, v110
	v_mul_f32_e32 v219, 0xbfb8aa3b, v111
	v_mul_f32_e32 v220, 0xbfb8aa3b, v100
	v_mul_f32_e32 v221, 0xbfb8aa3b, v101
	v_mul_f32_e32 v222, 0xbfb8aa3b, v102
	v_mul_f32_e32 v223, 0xbfb8aa3b, v103
	v_lshl_add_u64 v[202:203], v[200:201], 0, v[168:169]
	v_exp_f32_e32 v216, v216
	v_exp_f32_e32 v217, v217
	v_exp_f32_e32 v218, v218
	v_exp_f32_e32 v219, v219
	v_exp_f32_e32 v220, v220
	v_exp_f32_e32 v221, v221
	v_exp_f32_e32 v222, v222
	v_exp_f32_e32 v223, v223
	v_mov_b32_e32 v120, 0
	v_mov_b32_e32 v121, 0
	v_mov_b32_e32 v122, 0
	v_mov_b32_e32 v123, 0
	v_add_f32_e32 v216, 1.0, v216
	v_add_f32_e32 v217, 1.0, v217
	v_add_f32_e32 v218, 1.0, v218
	v_add_f32_e32 v219, 1.0, v219
	v_add_f32_e32 v220, 1.0, v220
	v_add_f32_e32 v221, 1.0, v221
	v_add_f32_e32 v222, 1.0, v222
	v_add_f32_e32 v223, 1.0, v223
	v_rcp_f32_e32 v216, v216
	v_rcp_f32_e32 v217, v217
	v_rcp_f32_e32 v218, v218
	v_rcp_f32_e32 v219, v219
	v_rcp_f32_e32 v220, v220
	v_rcp_f32_e32 v221, v221
	v_rcp_f32_e32 v222, v222
	v_rcp_f32_e32 v223, v223
	v_mul_f32_e32 v108, v108, v216
	v_mul_f32_e32 v109, v109, v217
	v_mul_f32_e32 v110, v110, v218
	v_mul_f32_e32 v111, v111, v219
	v_mul_f32_e32 v100, v100, v220
	v_mul_f32_e32 v101, v101, v221
	v_mul_f32_e32 v102, v102, v222
	v_mul_f32_e32 v103, v103, v223
	v_mul_f32_e32 v108, v108, v104
	v_mul_f32_e32 v109, v109, v105
	v_mul_f32_e32 v110, v110, v106
	v_mul_f32_e32 v111, v111, v107
	v_mul_f32_e32 v100, v100, v96
	v_mul_f32_e32 v101, v101, v97
	v_mul_f32_e32 v102, v102, v98
	v_mul_f32_e32 v103, v103, v99
	v_cvt_pk_bf16_f32 v104, v108, v109
	v_cvt_pk_bf16_f32 v105, v110, v111
	v_cvt_pk_bf16_f32 v106, v100, v101
	v_cvt_pk_bf16_f32 v107, v102, v103
	global_store_dwordx4 v[202:203], v[104:107], off
	v_mov_b32_e32 v108, 0
	v_mov_b32_e32 v109, 0
	v_mov_b32_e32 v110, 0
	v_mov_b32_e32 v111, 0
	v_mov_b32_e32 v100, 0
	v_mov_b32_e32 v101, 0
	v_mov_b32_e32 v102, 0
	v_mov_b32_e32 v103, 0
	v_mov_b32_e32 v96, 0
	v_mov_b32_e32 v97, 0
	v_mov_b32_e32 v98, 0
	v_mov_b32_e32 v99, 0
	v_mul_f32_e32 v190, 0xbfb8aa3b, v92
	v_mul_f32_e32 v191, 0xbfb8aa3b, v93
	v_mul_f32_e32 v192, 0xbfb8aa3b, v94
	v_mul_f32_e32 v193, 0xbfb8aa3b, v95
	v_mul_f32_e32 v194, 0xbfb8aa3b, v84
	v_mul_f32_e32 v195, 0xbfb8aa3b, v85
	v_mul_f32_e32 v196, 0xbfb8aa3b, v86
	v_mul_f32_e32 v197, 0xbfb8aa3b, v87
	v_lshl_add_u64 v[204:205], v[202:203], 0, v[168:169]
	v_exp_f32_e32 v190, v190
	v_exp_f32_e32 v191, v191
	v_exp_f32_e32 v192, v192
	v_exp_f32_e32 v193, v193
	v_exp_f32_e32 v194, v194
	v_exp_f32_e32 v195, v195
	v_exp_f32_e32 v196, v196
	v_exp_f32_e32 v197, v197
	v_mov_b32_e32 v104, 0
	v_mov_b32_e32 v105, 0
	v_mov_b32_e32 v106, 0
	v_mov_b32_e32 v107, 0
	v_add_f32_e32 v190, 1.0, v190
	v_add_f32_e32 v191, 1.0, v191
	v_add_f32_e32 v192, 1.0, v192
	v_add_f32_e32 v193, 1.0, v193
	v_add_f32_e32 v194, 1.0, v194
	v_add_f32_e32 v195, 1.0, v195
	v_add_f32_e32 v196, 1.0, v196
	v_add_f32_e32 v197, 1.0, v197
	v_rcp_f32_e32 v190, v190
	v_rcp_f32_e32 v191, v191
	v_rcp_f32_e32 v192, v192
	v_rcp_f32_e32 v193, v193
	v_rcp_f32_e32 v194, v194
	v_rcp_f32_e32 v195, v195
	v_rcp_f32_e32 v196, v196
	v_rcp_f32_e32 v197, v197
	v_mul_f32_e32 v92, v92, v190
	v_mul_f32_e32 v93, v93, v191
	v_mul_f32_e32 v94, v94, v192
	v_mul_f32_e32 v95, v95, v193
	v_mul_f32_e32 v84, v84, v194
	v_mul_f32_e32 v85, v85, v195
	v_mul_f32_e32 v86, v86, v196
	v_mul_f32_e32 v87, v87, v197
	v_mul_f32_e32 v92, v92, v88
	v_mul_f32_e32 v93, v93, v89
	v_mul_f32_e32 v94, v94, v90
	v_mul_f32_e32 v95, v95, v91
	v_mul_f32_e32 v84, v84, v80
	v_mul_f32_e32 v85, v85, v81
	v_mul_f32_e32 v86, v86, v82
	v_mul_f32_e32 v87, v87, v83
	v_cvt_pk_bf16_f32 v88, v92, v93
	v_cvt_pk_bf16_f32 v89, v94, v95
	v_cvt_pk_bf16_f32 v90, v84, v85
	v_cvt_pk_bf16_f32 v91, v86, v87
	global_store_dwordx4 v[204:205], v[88:91], off
	v_mov_b32_e32 v92, 0
	v_mov_b32_e32 v93, 0
	v_mov_b32_e32 v94, 0
	v_mov_b32_e32 v95, 0
	v_mov_b32_e32 v84, 0
	v_mov_b32_e32 v85, 0
	v_mov_b32_e32 v86, 0
	v_mov_b32_e32 v87, 0
	v_mov_b32_e32 v80, 0
	v_mov_b32_e32 v81, 0
	v_mov_b32_e32 v82, 0
	v_mov_b32_e32 v83, 0
	v_mul_f32_e32 v216, 0xbfb8aa3b, v76
	v_mul_f32_e32 v217, 0xbfb8aa3b, v77
	v_mul_f32_e32 v218, 0xbfb8aa3b, v78
	v_mul_f32_e32 v219, 0xbfb8aa3b, v79
	v_mul_f32_e32 v220, 0xbfb8aa3b, v68
	v_mul_f32_e32 v221, 0xbfb8aa3b, v69
	v_mul_f32_e32 v222, 0xbfb8aa3b, v70
	v_mul_f32_e32 v223, 0xbfb8aa3b, v71
	v_lshl_add_u64 v[206:207], v[204:205], 0, v[168:169]
	v_exp_f32_e32 v216, v216
	v_exp_f32_e32 v217, v217
	v_exp_f32_e32 v218, v218
	v_exp_f32_e32 v219, v219
	v_exp_f32_e32 v220, v220
	v_exp_f32_e32 v221, v221
	v_exp_f32_e32 v222, v222
	v_exp_f32_e32 v223, v223
	v_mov_b32_e32 v88, 0
	v_mov_b32_e32 v89, 0
	v_mov_b32_e32 v90, 0
	v_mov_b32_e32 v91, 0
	v_add_f32_e32 v216, 1.0, v216
	v_add_f32_e32 v217, 1.0, v217
	v_add_f32_e32 v218, 1.0, v218
	v_add_f32_e32 v219, 1.0, v219
	v_add_f32_e32 v220, 1.0, v220
	v_add_f32_e32 v221, 1.0, v221
	v_add_f32_e32 v222, 1.0, v222
	v_add_f32_e32 v223, 1.0, v223
	v_rcp_f32_e32 v216, v216
	v_rcp_f32_e32 v217, v217
	v_rcp_f32_e32 v218, v218
	v_rcp_f32_e32 v219, v219
	v_rcp_f32_e32 v220, v220
	v_rcp_f32_e32 v221, v221
	v_rcp_f32_e32 v222, v222
	v_rcp_f32_e32 v223, v223
	v_mul_f32_e32 v76, v76, v216
	v_mul_f32_e32 v77, v77, v217
	v_mul_f32_e32 v78, v78, v218
	v_mul_f32_e32 v79, v79, v219
	v_mul_f32_e32 v68, v68, v220
	v_mul_f32_e32 v69, v69, v221
	v_mul_f32_e32 v70, v70, v222
	v_mul_f32_e32 v71, v71, v223
	v_mul_f32_e32 v76, v76, v72
	v_mul_f32_e32 v77, v77, v73
	v_mul_f32_e32 v78, v78, v74
	v_mul_f32_e32 v79, v79, v75
	v_mul_f32_e32 v68, v68, v64
	v_mul_f32_e32 v69, v69, v65
	v_mul_f32_e32 v70, v70, v66
	v_mul_f32_e32 v71, v71, v67
	v_cvt_pk_bf16_f32 v72, v76, v77
	v_cvt_pk_bf16_f32 v73, v78, v79
	v_cvt_pk_bf16_f32 v74, v68, v69
	v_cvt_pk_bf16_f32 v75, v70, v71
	global_store_dwordx4 v[206:207], v[72:75], off
	v_mov_b32_e32 v76, 0
	v_mov_b32_e32 v77, 0
	v_mov_b32_e32 v78, 0
	v_mov_b32_e32 v79, 0
	v_mov_b32_e32 v68, 0
	v_mov_b32_e32 v69, 0
	v_mov_b32_e32 v70, 0
	v_mov_b32_e32 v71, 0
	v_mov_b32_e32 v64, 0
	v_mov_b32_e32 v65, 0
	v_mov_b32_e32 v66, 0
	v_mov_b32_e32 v67, 0
	v_mul_f32_e32 v190, 0xbfb8aa3b, v60
	v_mul_f32_e32 v191, 0xbfb8aa3b, v61
	v_mul_f32_e32 v192, 0xbfb8aa3b, v62
	v_mul_f32_e32 v193, 0xbfb8aa3b, v63
	v_mul_f32_e32 v194, 0xbfb8aa3b, v52
	v_mul_f32_e32 v195, 0xbfb8aa3b, v53
	v_mul_f32_e32 v196, 0xbfb8aa3b, v54
	v_mul_f32_e32 v197, 0xbfb8aa3b, v55
	v_lshl_add_u64 v[208:209], v[168:169], 3, v[200:201]
	v_exp_f32_e32 v190, v190
	v_exp_f32_e32 v191, v191
	v_exp_f32_e32 v192, v192
	v_exp_f32_e32 v193, v193
	v_exp_f32_e32 v194, v194
	v_exp_f32_e32 v195, v195
	v_exp_f32_e32 v196, v196
	v_exp_f32_e32 v197, v197
	v_mov_b32_e32 v72, 0
	v_mov_b32_e32 v73, 0
	v_mov_b32_e32 v74, 0
	v_mov_b32_e32 v75, 0
	v_add_f32_e32 v190, 1.0, v190
	v_add_f32_e32 v191, 1.0, v191
	v_add_f32_e32 v192, 1.0, v192
	v_add_f32_e32 v193, 1.0, v193
	v_add_f32_e32 v194, 1.0, v194
	v_add_f32_e32 v195, 1.0, v195
	v_add_f32_e32 v196, 1.0, v196
	v_add_f32_e32 v197, 1.0, v197
	v_rcp_f32_e32 v190, v190
	v_rcp_f32_e32 v191, v191
	v_rcp_f32_e32 v192, v192
	v_rcp_f32_e32 v193, v193
	v_rcp_f32_e32 v194, v194
	v_rcp_f32_e32 v195, v195
	v_rcp_f32_e32 v196, v196
	v_rcp_f32_e32 v197, v197
	v_mul_f32_e32 v60, v60, v190
	v_mul_f32_e32 v61, v61, v191
	v_mul_f32_e32 v62, v62, v192
	v_mul_f32_e32 v63, v63, v193
	v_mul_f32_e32 v52, v52, v194
	v_mul_f32_e32 v53, v53, v195
	v_mul_f32_e32 v54, v54, v196
	v_mul_f32_e32 v55, v55, v197
	v_mul_f32_e32 v60, v60, v56
	v_mul_f32_e32 v61, v61, v57
	v_mul_f32_e32 v62, v62, v58
	v_mul_f32_e32 v63, v63, v59
	v_mul_f32_e32 v52, v52, v48
	v_mul_f32_e32 v53, v53, v49
	v_mul_f32_e32 v54, v54, v50
	v_mul_f32_e32 v55, v55, v51
	v_cvt_pk_bf16_f32 v56, v60, v61
	v_cvt_pk_bf16_f32 v57, v62, v63
	v_cvt_pk_bf16_f32 v58, v52, v53
	v_cvt_pk_bf16_f32 v59, v54, v55
	global_store_dwordx4 v[208:209], v[56:59], off
	v_mov_b32_e32 v60, 0
	v_mov_b32_e32 v61, 0
	v_mov_b32_e32 v62, 0
	v_mov_b32_e32 v63, 0
	v_mov_b32_e32 v52, 0
	v_mov_b32_e32 v53, 0
	v_mov_b32_e32 v54, 0
	v_mov_b32_e32 v55, 0
	v_mov_b32_e32 v48, 0
	v_mov_b32_e32 v49, 0
	v_mov_b32_e32 v50, 0
	v_mov_b32_e32 v51, 0
	v_mul_f32_e32 v216, 0xbfb8aa3b, v44
	v_mul_f32_e32 v217, 0xbfb8aa3b, v45
	v_mul_f32_e32 v218, 0xbfb8aa3b, v46
	v_mul_f32_e32 v219, 0xbfb8aa3b, v47
	v_mul_f32_e32 v220, 0xbfb8aa3b, v36
	v_mul_f32_e32 v221, 0xbfb8aa3b, v37
	v_mul_f32_e32 v222, 0xbfb8aa3b, v38
	v_mul_f32_e32 v223, 0xbfb8aa3b, v39
	v_lshl_add_u64 v[210:211], v[208:209], 0, v[168:169]
	v_exp_f32_e32 v216, v216
	v_exp_f32_e32 v217, v217
	v_exp_f32_e32 v218, v218
	v_exp_f32_e32 v219, v219
	v_exp_f32_e32 v220, v220
	v_exp_f32_e32 v221, v221
	v_exp_f32_e32 v222, v222
	v_exp_f32_e32 v223, v223
	v_mov_b32_e32 v56, 0
	v_mov_b32_e32 v57, 0
	v_mov_b32_e32 v58, 0
	v_mov_b32_e32 v59, 0
	v_add_f32_e32 v216, 1.0, v216
	v_add_f32_e32 v217, 1.0, v217
	v_add_f32_e32 v218, 1.0, v218
	v_add_f32_e32 v219, 1.0, v219
	v_add_f32_e32 v220, 1.0, v220
	v_add_f32_e32 v221, 1.0, v221
	v_add_f32_e32 v222, 1.0, v222
	v_add_f32_e32 v223, 1.0, v223
	v_rcp_f32_e32 v216, v216
	v_rcp_f32_e32 v217, v217
	v_rcp_f32_e32 v218, v218
	v_rcp_f32_e32 v219, v219
	v_rcp_f32_e32 v220, v220
	v_rcp_f32_e32 v221, v221
	v_rcp_f32_e32 v222, v222
	v_rcp_f32_e32 v223, v223
	v_mul_f32_e32 v44, v44, v216
	v_mul_f32_e32 v45, v45, v217
	v_mul_f32_e32 v46, v46, v218
	v_mul_f32_e32 v47, v47, v219
	v_mul_f32_e32 v36, v36, v220
	v_mul_f32_e32 v37, v37, v221
	v_mul_f32_e32 v38, v38, v222
	v_mul_f32_e32 v39, v39, v223
	v_mul_f32_e32 v44, v44, v40
	v_mul_f32_e32 v45, v45, v41
	v_mul_f32_e32 v46, v46, v42
	v_mul_f32_e32 v47, v47, v43
	v_mul_f32_e32 v36, v36, v32
	v_mul_f32_e32 v37, v37, v33
	v_mul_f32_e32 v38, v38, v34
	v_mul_f32_e32 v39, v39, v35
	v_cvt_pk_bf16_f32 v40, v44, v45
	v_cvt_pk_bf16_f32 v41, v46, v47
	v_cvt_pk_bf16_f32 v42, v36, v37
	v_cvt_pk_bf16_f32 v43, v38, v39
	global_store_dwordx4 v[210:211], v[40:43], off
	v_mov_b32_e32 v44, 0
	v_mov_b32_e32 v45, 0
	v_mov_b32_e32 v46, 0
	v_mov_b32_e32 v47, 0
	v_mov_b32_e32 v36, 0
	v_mov_b32_e32 v37, 0
	v_mov_b32_e32 v38, 0
	v_mov_b32_e32 v39, 0
	v_mov_b32_e32 v32, 0
	v_mov_b32_e32 v33, 0
	v_mov_b32_e32 v34, 0
	v_mov_b32_e32 v35, 0
	v_mul_f32_e32 v190, 0xbfb8aa3b, v28
	v_mul_f32_e32 v191, 0xbfb8aa3b, v29
	v_mul_f32_e32 v192, 0xbfb8aa3b, v30
	v_mul_f32_e32 v193, 0xbfb8aa3b, v31
	v_mul_f32_e32 v194, 0xbfb8aa3b, v20
	v_mul_f32_e32 v195, 0xbfb8aa3b, v21
	v_mul_f32_e32 v196, 0xbfb8aa3b, v22
	v_mul_f32_e32 v197, 0xbfb8aa3b, v23
	v_lshl_add_u64 v[212:213], v[210:211], 0, v[168:169]
	v_exp_f32_e32 v190, v190
	v_exp_f32_e32 v191, v191
	v_exp_f32_e32 v192, v192
	v_exp_f32_e32 v193, v193
	v_exp_f32_e32 v194, v194
	v_exp_f32_e32 v195, v195
	v_exp_f32_e32 v196, v196
	v_exp_f32_e32 v197, v197
	v_mov_b32_e32 v40, 0
	v_mov_b32_e32 v41, 0
	v_mov_b32_e32 v42, 0
	v_mov_b32_e32 v43, 0
	v_add_f32_e32 v190, 1.0, v190
	v_add_f32_e32 v191, 1.0, v191
	v_add_f32_e32 v192, 1.0, v192
	v_add_f32_e32 v193, 1.0, v193
	v_add_f32_e32 v194, 1.0, v194
	v_add_f32_e32 v195, 1.0, v195
	v_add_f32_e32 v196, 1.0, v196
	v_add_f32_e32 v197, 1.0, v197
	v_rcp_f32_e32 v190, v190
	v_rcp_f32_e32 v191, v191
	v_rcp_f32_e32 v192, v192
	v_rcp_f32_e32 v193, v193
	v_rcp_f32_e32 v194, v194
	v_rcp_f32_e32 v195, v195
	v_rcp_f32_e32 v196, v196
	v_rcp_f32_e32 v197, v197
	v_mul_f32_e32 v28, v28, v190
	v_mul_f32_e32 v29, v29, v191
	v_mul_f32_e32 v30, v30, v192
	v_mul_f32_e32 v31, v31, v193
	v_mul_f32_e32 v20, v20, v194
	v_mul_f32_e32 v21, v21, v195
	v_mul_f32_e32 v22, v22, v196
	v_mul_f32_e32 v23, v23, v197
	v_mul_f32_e32 v28, v28, v24
	v_mul_f32_e32 v29, v29, v25
	v_mul_f32_e32 v30, v30, v26
	v_mul_f32_e32 v31, v31, v27
	v_mul_f32_e32 v20, v20, v16
	v_mul_f32_e32 v21, v21, v17
	v_mul_f32_e32 v22, v22, v18
	v_mul_f32_e32 v23, v23, v19
	v_cvt_pk_bf16_f32 v24, v28, v29
	v_cvt_pk_bf16_f32 v25, v30, v31
	v_cvt_pk_bf16_f32 v26, v20, v21
	v_cvt_pk_bf16_f32 v27, v22, v23
	global_store_dwordx4 v[212:213], v[24:27], off
	v_mov_b32_e32 v28, 0
	v_mov_b32_e32 v29, 0
	v_mov_b32_e32 v30, 0
	v_mov_b32_e32 v31, 0
	v_mov_b32_e32 v20, 0
	v_mov_b32_e32 v21, 0
	v_mov_b32_e32 v22, 0
	v_mov_b32_e32 v23, 0
	v_mov_b32_e32 v16, 0
	v_mov_b32_e32 v17, 0
	v_mov_b32_e32 v18, 0
	v_mov_b32_e32 v19, 0
	v_mul_f32_e32 v216, 0xbfb8aa3b, v12
	v_mul_f32_e32 v217, 0xbfb8aa3b, v13
	v_mul_f32_e32 v218, 0xbfb8aa3b, v14
	v_mul_f32_e32 v219, 0xbfb8aa3b, v15
	v_mul_f32_e32 v220, 0xbfb8aa3b, v4
	v_mul_f32_e32 v221, 0xbfb8aa3b, v5
	v_mul_f32_e32 v222, 0xbfb8aa3b, v6
	v_mul_f32_e32 v223, 0xbfb8aa3b, v7
	v_lshl_add_u64 v[214:215], v[212:213], 0, v[168:169]
	v_exp_f32_e32 v216, v216
	v_exp_f32_e32 v217, v217
	v_exp_f32_e32 v218, v218
	v_exp_f32_e32 v219, v219
	v_exp_f32_e32 v220, v220
	v_exp_f32_e32 v221, v221
	v_exp_f32_e32 v222, v222
	v_exp_f32_e32 v223, v223
	v_mov_b32_e32 v24, 0
	v_mov_b32_e32 v25, 0
	v_mov_b32_e32 v26, 0
	v_mov_b32_e32 v27, 0
	v_add_f32_e32 v216, 1.0, v216
	v_add_f32_e32 v217, 1.0, v217
	v_add_f32_e32 v218, 1.0, v218
	v_add_f32_e32 v219, 1.0, v219
	v_add_f32_e32 v220, 1.0, v220
	v_add_f32_e32 v221, 1.0, v221
	v_add_f32_e32 v222, 1.0, v222
	v_add_f32_e32 v223, 1.0, v223
	v_rcp_f32_e32 v216, v216
	v_rcp_f32_e32 v217, v217
	v_rcp_f32_e32 v218, v218
	v_rcp_f32_e32 v219, v219
	v_rcp_f32_e32 v220, v220
	v_rcp_f32_e32 v221, v221
	v_rcp_f32_e32 v222, v222
	v_rcp_f32_e32 v223, v223
	v_mul_f32_e32 v12, v12, v216
	v_mul_f32_e32 v13, v13, v217
	v_mul_f32_e32 v14, v14, v218
	v_mul_f32_e32 v15, v15, v219
	v_mul_f32_e32 v4, v4, v220
	v_mul_f32_e32 v5, v5, v221
	v_mul_f32_e32 v6, v6, v222
	v_mul_f32_e32 v7, v7, v223
	v_mul_f32_e32 v12, v12, v8
	v_mul_f32_e32 v13, v13, v9
	v_mul_f32_e32 v14, v14, v10
	v_mul_f32_e32 v15, v15, v11
	v_mul_f32_e32 v4, v4, v0
	v_mul_f32_e32 v5, v5, v1
	v_mul_f32_e32 v6, v6, v2
	v_mul_f32_e32 v7, v7, v3
	v_cvt_pk_bf16_f32 v8, v12, v13
	v_cvt_pk_bf16_f32 v9, v14, v15
	v_cvt_pk_bf16_f32 v10, v4, v5
	v_cvt_pk_bf16_f32 v11, v6, v7
	global_store_dwordx4 v[214:215], v[8:11], off
	v_mov_b32_e32 v12, 0
	v_mov_b32_e32 v13, 0
	v_mov_b32_e32 v14, 0
	v_mov_b32_e32 v15, 0
	v_mov_b32_e32 v4, 0
	v_mov_b32_e32 v5, 0
	v_mov_b32_e32 v6, 0
	v_mov_b32_e32 v7, 0
	v_mov_b32_e32 v0, 0
	v_mov_b32_e32 v1, 0
	v_mov_b32_e32 v2, 0
	v_mov_b32_e32 v3, 0
	s_mov_b64 s[0:1], -1
	v_mov_b32_e32 v8, 0
	v_mov_b32_e32 v9, 0
	v_mov_b32_e32 v10, 0
	v_mov_b32_e32 v11, 0
	s_andn2_b64 vcc, exec, s[36:37]
	s_cbranch_vccnz .LBB0_1327
	s_andn2_b64 vcc, exec, s[38:39]
	s_cbranch_vccnz .LBB0_1326
	s_barrier
	s_branch .LBB0_1326
